# v53 + norm1 row loop prefetches x two rows ahead (loop unrolled by two with alternating register sets)
# speedup vs baseline: 1.0283x; 1.0064x over previous
; __global__ void __launch_bounds__(NWAVES * 64, 2) fwd_kernel(Args args_unused) {
;     ...
;         { const int nrow = grouped ? (4 * SEQ + 4 * CTXL) : MT;
;           for (int r = gw; r < nrow; r += NGW) { const int mrow = (!grouped || r < 4 * SEQ) ? r : ML + (r - 4 * SEQ); P1_ROW(mrow); } }
.LBB0_170:
	s_cmp_lt_i32 s89, 2
	s_cselect_b64 s[10:11], -1, 0
	s_and_b64 s[0:1], s[10:11], s[20:21]
	s_andn2_b64 vcc, exec, s[0:1]
	s_cbranch_vccnz .LBB0_183
	v_mbcnt_lo_u32_b32 v128, -1, 0
	v_mbcnt_hi_u32_b32 v128, -1, v128
	s_load_dwordx2 s[12:13], s[96:97], 0xb0
	s_waitcnt lgkmcnt(0)
	s_load_dwordx2 s[4:5], s[96:97], 0
	s_waitcnt lgkmcnt(0)
	s_load_dwordx2 s[6:7], s[96:97], 16
	s_waitcnt lgkmcnt(0)
	s_movk_i32 s3, 0x4400
	s_and_b64 s[0:1], s[18:19], exec
	s_load_dwordx2 s[14:15], s[96:97], 48
	s_waitcnt lgkmcnt(0)
	s_mov_b32 s0, 0x8800
	s_cmp_ge_i32 s22, s0
	s_cbranch_scc1 .LBB0_178
	v_mbcnt_lo_u32_b32 v0, -1, 0
	v_mbcnt_hi_u32_b32 v0, -1, v0
	v_and_b32_e32 v1, 64, v0
	v_add_u32_e32 v1, 64, v1
	v_xor_b32_e32 v2, 1, v0
	v_cmp_lt_i32_e32 vcc, v2, v1
	v_lshlrev_b32_e32 v4, 2, v128
	v_ashrrev_i32_e32 v5, 31, v4
	v_cndmask_b32_e32 v2, v0, v2, vcc
	v_lshlrev_b32_e32 v6, 2, v2
	v_xor_b32_e32 v2, 2, v0
	v_cmp_lt_i32_e32 vcc, v2, v1
	s_mov_b64 s[16:17], 0x2000000
	s_mov_b32 s9, 0
	v_cndmask_b32_e32 v2, v0, v2, vcc
	v_lshlrev_b32_e32 v7, 2, v2
	v_xor_b32_e32 v2, 4, v0
	v_cmp_lt_i32_e32 vcc, v2, v1
	v_mov_b32_e32 v12, 0x358637bd
	s_mov_b32 s1, 0x800000
	v_cndmask_b32_e32 v2, v0, v2, vcc
	v_lshlrev_b32_e32 v8, 2, v2
	v_xor_b32_e32 v2, 8, v0
	v_cmp_lt_i32_e32 vcc, v2, v1
	s_movk_i32 s3, 0x1000
	s_add_i32 s37, s22, 1
	s_mul_i32 s37, s37, 17
	s_mov_b32 s56, -1
	s_mul_i32 s23, s22, 17
	s_cmp_eq_u32 s24, 0x800
	s_cselect_b32 s32, 1, s24
	s_cselect_b32 s23, s23, s22
	s_cselect_b32 s0, s37, s0
	v_cndmask_b32_e32 v2, v0, v2, vcc
	v_lshlrev_b32_e32 v9, 2, v2
	v_xor_b32_e32 v2, 16, v0
	v_cmp_lt_i32_e32 vcc, v2, v1
	s_nop 1
	v_cndmask_b32_e32 v2, v0, v2, vcc
	v_lshlrev_b32_e32 v10, 2, v2
	v_xor_b32_e32 v2, 32, v0
	v_cmp_lt_i32_e32 vcc, v2, v1
	s_nop 1
	v_cndmask_b32_e32 v0, v0, v2, vcc
	v_lshlrev_b32_e32 v11, 2, v0
	v_lshl_add_u64 v[0:1], v[4:5], 1, s[12:13]
	v_lshl_add_u64 v[0:1], v[0:1], 0, s[16:17]
	v_lshl_add_u64 v[2:3], v[4:5], 2, s[14:15]
	v_lshlrev_b64 v[4:5], 2, v[4:5]
	s_mov_b64 s[14:15], 0x1000
	s_mov_b32 s36, s23
	s_mov_b32 s34, s36
	s_cmpk_gt_i32 s34, 0x7fff
	s_cselect_b32 s20, s6, s4
	s_cselect_b32 s21, s7, s5
	s_cselect_b32 s8, 0x8000, 0
	s_sub_i32 s8, s34, s8
	s_lshl_b64 s[38:39], s[8:9], 12
	s_add_u32 s20, s20, s38
	s_addc_u32 s21, s21, s39
	v_lshl_add_u64 v[120:121], s[20:21], 0, v[4:5]
	global_load_dwordx4 v[104:107], v[120:121], off nt
	global_load_dwordx4 v[108:111], v[120:121], off offset:1024 nt
	global_load_dwordx4 v[112:115], v[120:121], off offset:3072 nt
	global_load_dwordx4 v[116:119], v[120:121], off offset:2048 nt
	s_add_i32 s36, s23, s32
	s_cmp_ge_i32 s36, s0
	s_cselect_b32 s36, s23, s36
	s_mov_b32 s34, s36
	s_cmpk_gt_i32 s34, 0x7fff
	s_cselect_b32 s20, s6, s4
	s_cselect_b32 s21, s7, s5
	s_cselect_b32 s8, 0x8000, 0
	s_sub_i32 s8, s34, s8
	s_lshl_b64 s[38:39], s[8:9], 12
	s_add_u32 s20, s20, s38
	s_addc_u32 s21, s21, s39
	v_lshl_add_u64 v[120:121], s[20:21], 0, v[4:5]
	global_load_dwordx4 v[130:133], v[120:121], off nt
	global_load_dwordx4 v[134:137], v[120:121], off offset:1024 nt
	global_load_dwordx4 v[138:141], v[120:121], off offset:3072 nt
	global_load_dwordx4 v[142:145], v[120:121], off offset:2048 nt
	s_mov_b32 s34, s23
.Lp1_loop:
	s_mov_b32 s34, s23
	s_mov_b32 s16, s34
	s_mov_b32 s17, 0
	s_min_i32 s8, s34, 0x8000
	s_ashr_i32 s8, s8, 12
	s_cmp_eq_u32 s8, s56
	s_cbranch_scc1 .Lp1_keep
	s_mov_b32 s56, s8
	s_mul_hi_i32 s21, s8, 0x6000
	s_mulk_i32 s8, 0x6000
	s_add_u32 s20, s12, s8
	s_addc_u32 s21, s13, s21
	v_lshl_add_u64 v[54:55], s[20:21], 0, v[4:5]
	v_add_co_u32_e32 v30, vcc, s3, v54
	v_lshl_add_u64 v[56:57], v[54:55], 0, s[14:15]
	s_nop 0
	v_addc_co_u32_e32 v31, vcc, 0, v55, vcc
	global_load_dwordx4 v[30:33], v[30:31], off
	s_nop 0
	global_load_dwordx4 v[34:37], v[56:57], off offset:1024
	global_load_dwordx4 v[38:41], v[2:3], off offset:1024
	global_load_dwordx4 v[42:45], v[2:3], off
	global_load_dwordx4 v[46:49], v[54:55], off offset:1024
	global_load_dwordx4 v[50:53], v[54:55], off
	global_load_dwordx4 v[80:83], v[56:57], off offset:2048
	global_load_dwordx4 v[84:87], v[2:3], off offset:2048
	global_load_dwordx4 v[88:91], v[56:57], off offset:3072
	global_load_dwordx4 v[92:95], v[2:3], off offset:3072
	global_load_dwordx4 v[96:99], v[54:55], off offset:2048
	global_load_dwordx4 v[100:103], v[54:55], off offset:3072
	s_branch .Lp1_join

.Lp1_join:
	s_waitcnt vmcnt(12)
	v_mov_b32_e32 v14, v104
	v_mov_b32_e32 v15, v105
	v_mov_b32_e32 v16, v106
	v_mov_b32_e32 v17, v107
	v_mov_b32_e32 v18, v108
	v_mov_b32_e32 v19, v109
	v_mov_b32_e32 v20, v110
	v_mov_b32_e32 v21, v111
	v_mov_b32_e32 v22, v112
	v_mov_b32_e32 v23, v113
	v_mov_b32_e32 v24, v114
	v_mov_b32_e32 v25, v115
	v_mov_b32_e32 v26, v116
	v_mov_b32_e32 v27, v117
	v_mov_b32_e32 v28, v118
	v_mov_b32_e32 v29, v119
	s_mov_b32 s37, s23
	s_add_i32 s23, s23, s32
	s_add_i32 s36, s23, s32
	s_cmp_ge_i32 s36, s0
	s_cselect_b32 s36, s37, s36
	s_cmp_ge_i32 s23, s0
	s_cselect_b32 s40, 1, 0
	s_mov_b32 s34, s36
	s_cmpk_gt_i32 s34, 0x7fff
	s_cselect_b32 s20, s6, s4
	s_cselect_b32 s21, s7, s5
	s_cselect_b32 s8, 0x8000, 0
	s_sub_i32 s8, s34, s8
	s_lshl_b64 s[38:39], s[8:9], 12
	s_add_u32 s20, s20, s38
	s_addc_u32 s21, s21, s39
	v_lshl_add_u64 v[120:121], s[20:21], 0, v[4:5]
	global_load_dwordx4 v[104:107], v[120:121], off nt
	global_load_dwordx4 v[108:111], v[120:121], off offset:1024 nt
	global_load_dwordx4 v[112:115], v[120:121], off offset:3072 nt
	global_load_dwordx4 v[116:119], v[120:121], off offset:2048 nt
	s_lshl_b64 s[16:17], s[16:17], 11
	v_pk_mul_f32 v[58:59], v[16:17], v[16:17]
	v_pk_mul_f32 v[60:61], v[14:15], v[14:15]
	v_pk_mul_f32 v[62:63], v[20:21], v[20:21]
	v_pk_mul_f32 v[64:65], v[18:19], v[18:19]
	v_pk_mov_b32 v[70:71], v[60:61], v[58:59] op_sel:[1,0]
	v_mov_b32_e32 v61, v59
	v_pk_mov_b32 v[58:59], v[64:65], v[62:63] op_sel:[1,0]
	v_mov_b32_e32 v65, v63
	v_mul_f32_e32 v69, v23, v23
	v_mul_f32_e32 v66, v27, v27
	v_mul_f32_e32 v68, v29, v29
	v_pk_add_f32 v[60:61], v[70:71], v[60:61]
	v_pk_add_f32 v[58:59], v[58:59], v[64:65]
	v_mul_f32_e32 v13, v22, v22
	v_mul_f32_e32 v72, v24, v24
	v_mul_f32_e32 v73, v25, v25
	v_pk_fma_f32 v[62:63], v[26:27], v[26:27], v[66:67] op_sel_hi:[1,1,0]
	v_pk_fma_f32 v[66:67], v[28:29], v[28:29], v[68:69] op_sel_hi:[1,1,0]
	v_pk_add_f32 v[60:61], v[60:61], v[60:61] op_sel:[0,1] op_sel_hi:[1,0]
	v_pk_add_f32 v[58:59], v[58:59], v[58:59] op_sel:[0,1] op_sel_hi:[1,0]
	v_mov_b32_e32 v63, v72
	v_mov_b32_e32 v67, v73
	v_mov_b32_e32 v61, v13
	v_mov_b32_e32 v59, v69
	v_pk_add_f32 v[62:63], v[62:63], v[66:67]
	v_pk_add_f32 v[58:59], v[60:61], v[58:59]
	s_waitcnt vmcnt(15)
	v_pk_add_f32 v[76:77], v[32:33], 1.0 op_sel_hi:[1,0]
	v_pk_add_f32 v[58:59], v[58:59], v[62:63]
	v_pk_add_f32 v[74:75], v[30:31], 1.0 op_sel_hi:[1,0]
	v_add_f32_e32 v13, v58, v59
	ds_bpermute_b32 v58, v6, v13
	s_waitcnt vmcnt(14)
	v_pk_add_f32 v[122:123], v[36:37], 1.0 op_sel_hi:[1,0]
	v_pk_add_f32 v[78:79], v[34:35], 1.0 op_sel_hi:[1,0]
	s_waitcnt lgkmcnt(0)
	v_add_f32_e32 v13, v13, v58
	ds_bpermute_b32 v58, v7, v13
	s_waitcnt lgkmcnt(0)
	v_add_f32_e32 v13, v13, v58
	ds_bpermute_b32 v58, v8, v13
	s_waitcnt lgkmcnt(0)
	v_add_f32_e32 v13, v13, v58
	ds_bpermute_b32 v58, v9, v13
	s_waitcnt lgkmcnt(0)
	v_add_f32_e32 v13, v13, v58
	ds_bpermute_b32 v58, v10, v13
	s_waitcnt lgkmcnt(0)
	v_add_f32_e32 v13, v13, v58
	ds_bpermute_b32 v60, v11, v13
	v_lshl_add_u64 v[58:59], v[0:1], 0, s[16:17]
	s_waitcnt lgkmcnt(0)
	v_add_f32_e32 v13, v13, v60
	v_fmamk_f32 v13, v13, 0x3a800000, v12
	v_mul_f32_e32 v60, 0x4b800000, v13
	v_cmp_gt_f32_e32 vcc, s1, v13
	s_nop 1
	v_cndmask_b32_e32 v13, v13, v60, vcc
	v_rsq_f32_e32 v13, v13
	s_nop 0
	v_mul_f32_e32 v60, 0x45800000, v13
	v_cndmask_b32_e32 v60, v13, v60, vcc
	v_pk_mul_f32 v[16:17], v[60:61], v[16:17] op_sel_hi:[0,1]
	v_pk_mul_f32 v[14:15], v[60:61], v[14:15] op_sel_hi:[0,1]
	v_pk_mul_f32 v[20:21], v[60:61], v[20:21] op_sel_hi:[0,1]
	v_pk_mul_f32 v[18:19], v[60:61], v[18:19] op_sel_hi:[0,1]
	s_waitcnt vmcnt(12)
	v_pk_mul_f32 v[14:15], v[42:43], v[14:15]
	v_pk_mul_f32 v[16:17], v[44:45], v[16:17]
	v_pk_mul_f32 v[18:19], v[38:39], v[18:19]
	v_pk_mul_f32 v[20:21], v[40:41], v[20:21]
	s_waitcnt vmcnt(10)
	v_pk_fma_f32 v[16:17], v[76:77], v[16:17], v[52:53]
	v_pk_fma_f32 v[14:15], v[74:75], v[14:15], v[50:51]
	v_pk_fma_f32 v[20:21], v[122:123], v[20:21], v[48:49]
	v_pk_fma_f32 v[18:19], v[78:79], v[18:19], v[46:47]
	v_cvt_pk_bf16_f32 v14, v14, v15
	v_cvt_pk_bf16_f32 v15, v16, v17
	v_cvt_pk_bf16_f32 v16, v18, v19
	v_cvt_pk_bf16_f32 v17, v20, v21
	global_store_dwordx2 v[58:59], v[14:15], off sc1
	global_store_dwordx2 v[58:59], v[16:17], off offset:512 sc1
	v_pk_mul_f32 v[28:29], v[60:61], v[28:29] op_sel_hi:[0,1]
	v_pk_mul_f32 v[26:27], v[60:61], v[26:27] op_sel_hi:[0,1]
	v_pk_mul_f32 v[24:25], v[60:61], v[24:25] op_sel_hi:[0,1]
	v_pk_mul_f32 v[22:23], v[60:61], v[22:23] op_sel_hi:[0,1]
	s_waitcnt vmcnt(11)
	v_pk_add_f32 v[16:17], v[82:83], 1.0 op_sel_hi:[1,0]
	v_pk_add_f32 v[14:15], v[80:81], 1.0 op_sel_hi:[1,0]
	s_waitcnt vmcnt(10)
	v_pk_mul_f32 v[18:19], v[84:85], v[26:27]
	v_pk_mul_f32 v[20:21], v[86:87], v[28:29]
	s_waitcnt vmcnt(9)
	v_pk_add_f32 v[26:27], v[90:91], 1.0 op_sel_hi:[1,0]
	v_pk_add_f32 v[28:29], v[88:89], 1.0 op_sel_hi:[1,0]
	s_waitcnt vmcnt(8)
	v_pk_mul_f32 v[22:23], v[92:93], v[22:23]
	v_pk_mul_f32 v[24:25], v[94:95], v[24:25]
	s_waitcnt vmcnt(7)
	v_pk_fma_f32 v[16:17], v[16:17], v[20:21], v[98:99]
	v_pk_fma_f32 v[14:15], v[14:15], v[18:19], v[96:97]
	s_waitcnt vmcnt(6)
	v_pk_fma_f32 v[18:19], v[26:27], v[24:25], v[102:103]
	v_pk_fma_f32 v[20:21], v[28:29], v[22:23], v[100:101]
	v_cvt_pk_bf16_f32 v14, v14, v15
	v_cvt_pk_bf16_f32 v15, v16, v17
	v_cvt_pk_bf16_f32 v16, v20, v21
	v_cvt_pk_bf16_f32 v17, v18, v19
	global_store_dwordx2 v[58:59], v[14:15], off offset:1024 sc1
	global_store_dwordx2 v[58:59], v[16:17], off offset:1536 sc1
	s_cmp_lg_u32 s40, 0
	s_cbranch_scc0 .Lp1_loopB
	s_branch .Lp1_exit

.Lp1_joinB:
	s_waitcnt vmcnt(12)
	v_mov_b32_e32 v14, v130
	v_mov_b32_e32 v15, v131
	v_mov_b32_e32 v16, v132
	v_mov_b32_e32 v17, v133
	v_mov_b32_e32 v18, v134
	v_mov_b32_e32 v19, v135
	v_mov_b32_e32 v20, v136
	v_mov_b32_e32 v21, v137
	v_mov_b32_e32 v22, v138
	v_mov_b32_e32 v23, v139
	v_mov_b32_e32 v24, v140
	v_mov_b32_e32 v25, v141
	v_mov_b32_e32 v26, v142
	v_mov_b32_e32 v27, v143
	v_mov_b32_e32 v28, v144
	v_mov_b32_e32 v29, v145
	s_mov_b32 s37, s23
	s_add_i32 s23, s23, s32
	s_add_i32 s36, s23, s32
	s_cmp_ge_i32 s36, s0
	s_cselect_b32 s36, s37, s36
	s_cmp_ge_i32 s23, s0
	s_cselect_b32 s40, 1, 0
	s_mov_b32 s34, s36
	s_cmpk_gt_i32 s34, 0x7fff
	s_cselect_b32 s20, s6, s4
	s_cselect_b32 s21, s7, s5
	s_cselect_b32 s8, 0x8000, 0
	s_sub_i32 s8, s34, s8
	s_lshl_b64 s[38:39], s[8:9], 12
	s_add_u32 s20, s20, s38
	s_addc_u32 s21, s21, s39
	v_lshl_add_u64 v[120:121], s[20:21], 0, v[4:5]
	global_load_dwordx4 v[130:133], v[120:121], off nt
	global_load_dwordx4 v[134:137], v[120:121], off offset:1024 nt
	global_load_dwordx4 v[138:141], v[120:121], off offset:3072 nt
	global_load_dwordx4 v[142:145], v[120:121], off offset:2048 nt
	s_lshl_b64 s[16:17], s[16:17], 11
	v_pk_mul_f32 v[58:59], v[16:17], v[16:17]
	v_pk_mul_f32 v[60:61], v[14:15], v[14:15]
	v_pk_mul_f32 v[62:63], v[20:21], v[20:21]
	v_pk_mul_f32 v[64:65], v[18:19], v[18:19]
	v_pk_mov_b32 v[70:71], v[60:61], v[58:59] op_sel:[1,0]
	v_mov_b32_e32 v61, v59
	v_pk_mov_b32 v[58:59], v[64:65], v[62:63] op_sel:[1,0]
	v_mov_b32_e32 v65, v63
	v_mul_f32_e32 v69, v23, v23
	v_mul_f32_e32 v66, v27, v27
	v_mul_f32_e32 v68, v29, v29
	v_pk_add_f32 v[60:61], v[70:71], v[60:61]
	v_pk_add_f32 v[58:59], v[58:59], v[64:65]
	v_mul_f32_e32 v13, v22, v22
	v_mul_f32_e32 v72, v24, v24
	v_mul_f32_e32 v73, v25, v25
	v_pk_fma_f32 v[62:63], v[26:27], v[26:27], v[66:67] op_sel_hi:[1,1,0]
	v_pk_fma_f32 v[66:67], v[28:29], v[28:29], v[68:69] op_sel_hi:[1,1,0]
	v_pk_add_f32 v[60:61], v[60:61], v[60:61] op_sel:[0,1] op_sel_hi:[1,0]
	v_pk_add_f32 v[58:59], v[58:59], v[58:59] op_sel:[0,1] op_sel_hi:[1,0]
	v_mov_b32_e32 v63, v72
	v_mov_b32_e32 v67, v73
	v_mov_b32_e32 v61, v13
	v_mov_b32_e32 v59, v69
	v_pk_add_f32 v[62:63], v[62:63], v[66:67]
	v_pk_add_f32 v[58:59], v[60:61], v[58:59]
	s_waitcnt vmcnt(15)
	v_pk_add_f32 v[76:77], v[32:33], 1.0 op_sel_hi:[1,0]
	v_pk_add_f32 v[58:59], v[58:59], v[62:63]
	v_pk_add_f32 v[74:75], v[30:31], 1.0 op_sel_hi:[1,0]
	v_add_f32_e32 v13, v58, v59
	ds_bpermute_b32 v58, v6, v13
	s_waitcnt vmcnt(14)
	v_pk_add_f32 v[122:123], v[36:37], 1.0 op_sel_hi:[1,0]
	v_pk_add_f32 v[78:79], v[34:35], 1.0 op_sel_hi:[1,0]
	s_waitcnt lgkmcnt(0)
	v_add_f32_e32 v13, v13, v58
	ds_bpermute_b32 v58, v7, v13
	s_waitcnt lgkmcnt(0)
	v_add_f32_e32 v13, v13, v58
	ds_bpermute_b32 v58, v8, v13
	s_waitcnt lgkmcnt(0)
	v_add_f32_e32 v13, v13, v58
	ds_bpermute_b32 v58, v9, v13
	s_waitcnt lgkmcnt(0)
	v_add_f32_e32 v13, v13, v58
	ds_bpermute_b32 v58, v10, v13
	s_waitcnt lgkmcnt(0)
	v_add_f32_e32 v13, v13, v58
	ds_bpermute_b32 v60, v11, v13
	v_lshl_add_u64 v[58:59], v[0:1], 0, s[16:17]
	s_waitcnt lgkmcnt(0)
	v_add_f32_e32 v13, v13, v60
	v_fmamk_f32 v13, v13, 0x3a800000, v12
	v_mul_f32_e32 v60, 0x4b800000, v13
	v_cmp_gt_f32_e32 vcc, s1, v13
	s_nop 1
	v_cndmask_b32_e32 v13, v13, v60, vcc
	v_rsq_f32_e32 v13, v13
	s_nop 0
	v_mul_f32_e32 v60, 0x45800000, v13
	v_cndmask_b32_e32 v60, v13, v60, vcc
	v_pk_mul_f32 v[16:17], v[60:61], v[16:17] op_sel_hi:[0,1]
	v_pk_mul_f32 v[14:15], v[60:61], v[14:15] op_sel_hi:[0,1]
	v_pk_mul_f32 v[20:21], v[60:61], v[20:21] op_sel_hi:[0,1]
	v_pk_mul_f32 v[18:19], v[60:61], v[18:19] op_sel_hi:[0,1]
	s_waitcnt vmcnt(12)
	v_pk_mul_f32 v[14:15], v[42:43], v[14:15]
	v_pk_mul_f32 v[16:17], v[44:45], v[16:17]
	v_pk_mul_f32 v[18:19], v[38:39], v[18:19]
	v_pk_mul_f32 v[20:21], v[40:41], v[20:21]
	s_waitcnt vmcnt(10)
	v_pk_fma_f32 v[16:17], v[76:77], v[16:17], v[52:53]
	v_pk_fma_f32 v[14:15], v[74:75], v[14:15], v[50:51]
	v_pk_fma_f32 v[20:21], v[122:123], v[20:21], v[48:49]
	v_pk_fma_f32 v[18:19], v[78:79], v[18:19], v[46:47]
	v_cvt_pk_bf16_f32 v14, v14, v15
	v_cvt_pk_bf16_f32 v15, v16, v17
	v_cvt_pk_bf16_f32 v16, v18, v19
	v_cvt_pk_bf16_f32 v17, v20, v21
	global_store_dwordx2 v[58:59], v[14:15], off sc1
	global_store_dwordx2 v[58:59], v[16:17], off offset:512 sc1
	v_pk_mul_f32 v[28:29], v[60:61], v[28:29] op_sel_hi:[0,1]
	v_pk_mul_f32 v[26:27], v[60:61], v[26:27] op_sel_hi:[0,1]
	v_pk_mul_f32 v[24:25], v[60:61], v[24:25] op_sel_hi:[0,1]
	v_pk_mul_f32 v[22:23], v[60:61], v[22:23] op_sel_hi:[0,1]
	s_waitcnt vmcnt(11)
	v_pk_add_f32 v[16:17], v[82:83], 1.0 op_sel_hi:[1,0]
	v_pk_add_f32 v[14:15], v[80:81], 1.0 op_sel_hi:[1,0]
	s_waitcnt vmcnt(10)
	v_pk_mul_f32 v[18:19], v[84:85], v[26:27]
	v_pk_mul_f32 v[20:21], v[86:87], v[28:29]
	s_waitcnt vmcnt(9)
	v_pk_add_f32 v[26:27], v[90:91], 1.0 op_sel_hi:[1,0]
	v_pk_add_f32 v[28:29], v[88:89], 1.0 op_sel_hi:[1,0]
	s_waitcnt vmcnt(8)
	v_pk_mul_f32 v[22:23], v[92:93], v[22:23]
	v_pk_mul_f32 v[24:25], v[94:95], v[24:25]
	s_waitcnt vmcnt(7)
	v_pk_fma_f32 v[16:17], v[16:17], v[20:21], v[98:99]
	v_pk_fma_f32 v[14:15], v[14:15], v[18:19], v[96:97]
	s_waitcnt vmcnt(6)
	v_pk_fma_f32 v[18:19], v[26:27], v[24:25], v[102:103]
	v_pk_fma_f32 v[20:21], v[28:29], v[22:23], v[100:101]
	v_cvt_pk_bf16_f32 v14, v14, v15
	v_cvt_pk_bf16_f32 v15, v16, v17
	v_cvt_pk_bf16_f32 v16, v20, v21
	v_cvt_pk_bf16_f32 v17, v18, v19
	global_store_dwordx2 v[58:59], v[14:15], off offset:1024 sc1
	global_store_dwordx2 v[58:59], v[16:17], off offset:1536 sc1
	s_cmp_lg_u32 s40, 0
	s_cbranch_scc0 .Lp1_loop
; __global__ void __launch_bounds__(NWAVES * 64, 2) fwd_kernel(Args args_unused) {
;     ...
;         { const bf16_t* Wgu = (const bf16_t*)(ws + WS_WGU); float* beta = (float*)(ws + WS_BETA);
;           f32x4 sh[8][4];
; #pragma unroll
;           for (int bb = 0; bb < 8; ++bb)
; #pragma unroll
;               for (int q = 0; q < 4; ++q) sh[bb][q] = *(const f32x4*)(mod + (size_t)bb * NMOD + 3 * DM + lane * 16 + 4 * q);
;           for (int it = gw; it < 2 * FFH; it += NGW) {
;               const u32x4 wa = *(const u32x4*)(Wgu + (size_t)it * DM + lane * 16), wb = *(const u32x4*)(Wgu + (size_t)it * DM + lane * 16 + 8);
.Lp1_exit:
	s_waitcnt vmcnt(0)
.LBB0_178:
	s_cmpk_lt_i32 s22, 0x1600
	s_cbranch_scc0 .LBB0_183
	v_lshlrev_b32_e32 v130, 4, v128
	v_ashrrev_i32_e32 v131, 31, v130
	v_lshl_add_u64 v[104:105], v[130:131], 2, s[12:13]
	v_add_co_u32_e32 v18, vcc, 0x2d000, v104
	s_mov_b64 s[0:1], 0x2d000
	s_nop 0
	v_addc_co_u32_e32 v19, vcc, 0, v105, vcc
	v_add_co_u32_e32 v34, vcc, 0x27000, v104
	v_lshl_add_u64 v[16:17], v[104:105], 0, s[0:1]
	s_nop 0
	v_addc_co_u32_e32 v35, vcc, 0, v105, vcc
	v_add_co_u32_e32 v50, vcc, 0x21000, v104
	s_mov_b64 s[0:1], 0x27000
	s_nop 0
	v_addc_co_u32_e32 v51, vcc, 0, v105, vcc
	v_add_co_u32_e32 v66, vcc, 0x1b000, v104
	v_lshl_add_u64 v[32:33], v[104:105], 0, s[0:1]
	s_nop 0
	v_addc_co_u32_e32 v67, vcc, 0, v105, vcc
	v_add_co_u32_e32 v82, vcc, 0x15000, v104
	s_mov_b64 s[0:1], 0x21000
	s_nop 0
	v_addc_co_u32_e32 v83, vcc, 0, v105, vcc
	v_lshl_add_u64 v[48:49], v[104:105], 0, s[0:1]
	s_mov_b64 s[0:1], 0x1b000
	v_add_co_u32_e32 v98, vcc, 0xf000, v104
	v_lshl_add_u64 v[64:65], v[104:105], 0, s[0:1]
	s_mov_b64 s[0:1], 0x15000
	v_addc_co_u32_e32 v99, vcc, 0, v105, vcc
	v_lshl_add_u64 v[80:81], v[104:105], 0, s[0:1]
	s_mov_b64 s[0:1], 0xf000
	v_add_co_u32_e32 v106, vcc, 0x9000, v104
	v_lshl_add_u64 v[96:97], v[104:105], 0, s[0:1]
	s_mov_b64 s[0:1], 0x9000
	v_addc_co_u32_e32 v107, vcc, 0, v105, vcc
	v_lshl_add_u64 v[116:117], v[104:105], 0, s[0:1]
	s_mov_b64 s[0:1], 0x3000
	v_add_co_u32_e32 v118, vcc, 0x3000, v104
	v_lshl_add_u64 v[124:125], v[104:105], 0, s[0:1]
	s_nop 0
	v_addc_co_u32_e32 v119, vcc, 0, v105, vcc
	global_load_dwordx4 v[0:3], v[18:19], off nt
	global_load_dwordx4 v[4:7], v[16:17], off offset:48 nt
	global_load_dwordx4 v[8:11], v[16:17], off offset:32 nt
	global_load_dwordx4 v[12:15], v[16:17], off offset:16 nt
	s_nop 0
	global_load_dwordx4 v[16:19], v[34:35], off nt
	global_load_dwordx4 v[20:23], v[32:33], off offset:48 nt
	global_load_dwordx4 v[24:27], v[32:33], off offset:32 nt
	global_load_dwordx4 v[28:31], v[32:33], off offset:16 nt
	s_nop 0
	global_load_dwordx4 v[32:35], v[50:51], off nt
	global_load_dwordx4 v[36:39], v[48:49], off offset:48 nt
	global_load_dwordx4 v[40:43], v[48:49], off offset:32 nt
	global_load_dwordx4 v[44:47], v[48:49], off offset:16 nt
	s_nop 0
	global_load_dwordx4 v[48:51], v[66:67], off nt
	global_load_dwordx4 v[52:55], v[64:65], off offset:48 nt
	global_load_dwordx4 v[56:59], v[64:65], off offset:32 nt
	global_load_dwordx4 v[60:63], v[64:65], off offset:16 nt
	s_nop 0
	global_load_dwordx4 v[64:67], v[82:83], off nt
	global_load_dwordx4 v[68:71], v[80:81], off offset:48 nt
	global_load_dwordx4 v[72:75], v[80:81], off offset:32 nt
	global_load_dwordx4 v[76:79], v[80:81], off offset:16 nt
	s_nop 0
	global_load_dwordx4 v[80:83], v[98:99], off nt
	global_load_dwordx4 v[84:87], v[96:97], off offset:48 nt
	global_load_dwordx4 v[88:91], v[96:97], off offset:32 nt
	global_load_dwordx4 v[92:95], v[96:97], off offset:16 nt
	s_nop 0
	global_load_dwordx4 v[96:99], v[106:107], off nt
	global_load_dwordx4 v[100:103], v[116:117], off offset:48 nt
	s_nop 0
	global_load_dwordx4 v[104:107], v[116:117], off offset:32 nt
	global_load_dwordx4 v[108:111], v[116:117], off offset:16 nt
	global_load_dwordx4 v[112:115], v[118:119], off nt
	s_nop 0
	global_load_dwordx4 v[116:119], v[124:125], off offset:48 nt
	global_load_dwordx4 v[120:123], v[124:125], off offset:32 nt
	s_nop 0
	global_load_dwordx4 v[124:127], v[124:125], off offset:16 nt
	v_and_b32_e32 v129, 1, v128
	v_cmp_eq_u32_e32 vcc, 0, v129
	v_and_b32_e32 v129, 2, v128
	v_cmp_eq_u32_e64 s[8:9], 0, v129
	v_and_b32_e32 v129, 4, v128
	v_cmp_eq_u32_e64 s[4:5], 0, v129
	v_mbcnt_lo_u32_b32 v129, -1, 0
	v_mbcnt_hi_u32_b32 v129, -1, v129
	v_and_b32_e32 v133, 64, v129
	v_xor_b32_e32 v132, 1, v129
	v_add_u32_e32 v133, 64, v133
	v_cmp_lt_i32_e64 s[6:7], v132, v133
	s_ashr_i32 s23, s22, 31
	s_lshl_b64 s[0:1], s[22:23], 2
	v_cndmask_b32_e64 v132, v129, v132, s[6:7]
	v_lshlrev_b32_e32 v148, 2, v132
	v_xor_b32_e32 v132, 2, v129
	v_cmp_lt_i32_e64 s[6:7], v132, v133
	s_add_u32 s0, s12, s0
	s_addc_u32 s1, s13, s1
	v_cndmask_b32_e64 v132, v129, v132, s[6:7]
	v_lshlrev_b32_e32 v149, 2, v132
	v_xor_b32_e32 v132, 4, v129
	v_cmp_lt_i32_e64 s[6:7], v132, v133
	s_movk_i32 s3, 0x5800
	s_ashr_i32 s25, s24, 31
	v_cndmask_b32_e64 v132, v129, v132, s[6:7]
	v_lshlrev_b32_e32 v150, 2, v132
	v_xor_b32_e32 v132, 8, v129
	v_cmp_lt_i32_e64 s[6:7], v132, v133
	s_lshl_b64 s[14:15], s[24:25], 2
	s_nop 0
	v_cndmask_b32_e64 v132, v129, v132, s[6:7]
	v_lshlrev_b32_e32 v151, 2, v132
	v_xor_b32_e32 v132, 16, v129
	v_cmp_lt_i32_e64 s[6:7], v132, v133
	s_nop 1
	v_cndmask_b32_e64 v132, v129, v132, s[6:7]
	v_lshlrev_b32_e32 v152, 2, v132
	v_xor_b32_e32 v132, 32, v129
	v_cmp_lt_i32_e64 s[6:7], v132, v133
	s_nop 1
	v_cndmask_b32_e64 v129, v129, v132, s[6:7]
	v_cmp_gt_i32_e64 s[6:7], 8, v128
	v_bfrev_b32_e32 v128, v128
	v_lshlrev_b32_e32 v153, 2, v129
	v_lshrrev_b32_e32 v132, 29, v128
	v_mov_b64_e32 v[128:129], s[0:1]
	v_mad_u64_u32 v[128:129], s[0:1], v132, s3, v[128:129]
	s_mov_b64 s[0:1], 0xc8000
	s_nop 0
	v_lshl_add_u64 v[128:129], v[128:129], 0, s[0:1]
	s_lshl_b64 s[0:1], s[22:23], 11
	s_add_u32 s0, s12, s0
	s_addc_u32 s1, s13, s1
	v_lshl_add_u64 v[130:131], v[130:131], 1, s[0:1]
	s_mov_b64 s[0:1], 0x900010
	v_lshl_add_u64 v[130:131], v[130:131], 0, s[0:1]
	s_lshl_b64 s[12:13], s[24:25], 11
	s_branch .LBB0_181
